# speedup vs baseline: 1.0022x; 1.0022x over previous
; __device__ __forceinline__ unsigned xb_ld(unsigned* p)              { return __hip_atomic_load(p, __ATOMIC_RELAXED, __HIP_MEMORY_SCOPE_AGENT); }
; __device__ __forceinline__ void xcd_barrier_complete(unsigned* bar, unsigned x, unsigned& nloc, unsigned& nx) {
;     const unsigned G = gridDim.x * gridDim.y * gridDim.z;
;     unsigned sum, cnt, mine, sp = 0u;
;     for (;;) {
;         sum = 0u; cnt = 0u; mine = 0u;
; #pragma unroll
;         for (unsigned j = 0; j < 16; ++j) { const unsigned c = xb_ld(&bar[XB_XCNT(j)]); sum += c; cnt += (c > 0u) ? 1u : 0u; mine = (j == x) ? c : mine; }
;         if (sum == G) break;
;         __builtin_amdgcn_s_sleep(1);
;         if ((++sp & 255u) == 0u) { if (xb_ld(&bar[XB_TMO])) break; if (sp > XB_SPIN_CAP) { atomicAdd(&bar[XB_TMO], 1u); break; } }
;     }
;     nloc = mine > 0u ? mine : 1u; nx = cnt > 0u ? cnt : 1u;
; }
.LBB0_123:
	flat_load_dword v48, v[2:3] sc1
	flat_load_dword v1, v[4:5] sc1
	flat_load_dword v34, v[6:7] sc1
	flat_load_dword v35, v[8:9] sc1
	flat_load_dword v36, v[10:11] sc1
	flat_load_dword v37, v[12:13] sc1
	flat_load_dword v38, v[14:15] sc1
	flat_load_dword v39, v[16:17] sc1
	flat_load_dword v40, v[18:19] sc1
	flat_load_dword v41, v[20:21] sc1
	flat_load_dword v42, v[22:23] sc1
	flat_load_dword v43, v[24:25] sc1
	flat_load_dword v44, v[26:27] sc1
	flat_load_dword v45, v[28:29] sc1
	flat_load_dword v46, v[30:31] sc1
	flat_load_dword v47, v[32:33] sc1
	s_or_b64 s[12:13], s[12:13], exec
	s_or_b64 s[10:11], s[10:11], exec
	s_waitcnt vmcnt(0) lgkmcnt(0)
	v_add_u32_e32 v49, v1, v48
	v_add_u32_e32 v49, v49, v34
	v_add_u32_e32 v49, v49, v35
	v_add_u32_e32 v49, v49, v36
	v_add_u32_e32 v49, v49, v37
	v_add_u32_e32 v49, v49, v38
	v_add_u32_e32 v49, v49, v39
	v_add_u32_e32 v49, v49, v40
	v_add_u32_e32 v49, v49, v41
	v_add_u32_e32 v49, v49, v42
	v_add_u32_e32 v49, v49, v43
	v_add_u32_e32 v49, v49, v44
	v_add_u32_e32 v49, v49, v45
	v_add_u32_e32 v49, v49, v46
	v_add_u32_e32 v49, v49, v47
	v_cmp_ne_u32_e32 vcc, s22, v49
	s_and_saveexec_b64 s[14:15], vcc
	s_cbranch_execz .LBB0_122
	s_and_b32 s0, s23, 0xff
	s_mov_b64 s[16:17], -1
	s_cmp_eq_u32 s0, 0
	s_mov_b64 s[18:19], -1
	s_mov_b64 s[0:1], -1
	s_nop 0
	s_cbranch_scc1 .LBB0_126
	s_and_saveexec_b64 s[20:21], s[18:19]
	s_cbranch_execz .LBB0_121
	s_branch .LBB0_129

; __device__ __forceinline__ unsigned xb_ld(unsigned* p)              { return __hip_atomic_load(p, __ATOMIC_RELAXED, __HIP_MEMORY_SCOPE_AGENT); }
; __device__ __forceinline__ unsigned xb_add(unsigned* p, unsigned v) { return __hip_atomic_fetch_add(p, v, __ATOMIC_RELAXED, __HIP_MEMORY_SCOPE_AGENT); }
; #define XB_SPIN(cond, bar) do { unsigned _sp = 0; while (cond) { __builtin_amdgcn_s_sleep(1); \
;     if ((++_sp & 255u) == 0u) { if (xb_ld(&(bar)[XB_TMO])) break; if (_sp > XB_SPIN_CAP) { atomicAdd(&(bar)[XB_TMO], 1u); break; } } } } while (0)
; __device__ __forceinline__ void xcd_barrier(const XcdBarrier& b) {
;     ...
;             else XB_SPIN(xb_ld(&bar[XB_TOPGEN]) == tg, bar);
;             __builtin_amdgcn_fence(__ATOMIC_ACQUIRE, "agent");
;             xb_add(&bar[XB_XGEN(b.x)], 1u);
;             asm volatile("s_waitcnt vmcnt(0)" ::: "memory");
;         } else {
;             XB_SPIN(xb_ld(&bar[XB_XGEN(b.x)]) == gen, bar);
.LBB0_137:
	s_and_b32 s0, s26, 0xff
	s_mov_b64 s[18:19], -1
	s_cmp_lg_u32 s0, 0
	s_mov_b64 s[0:1], -1
	s_nop 0
	s_cbranch_scc1 .LBB0_141
	v_mov_b64_e32 v[2:3], s[8:9]
	flat_load_dword v2, v[2:3] sc1
	s_mov_b64 s[0:1], 0
	s_mov_b64 s[20:21], -1
	s_waitcnt vmcnt(0) lgkmcnt(0)
	v_cmp_eq_u32_e32 vcc, 0, v2
	s_and_saveexec_b64 s[22:23], vcc
	s_cmp_lt_u32 s26, 0x40001
	s_cselect_b64 s[0:1], -1, 0
	s_xor_b64 s[20:21], exec, -1
	s_and_b64 s[0:1], s[0:1], exec
	s_or_b64 exec, exec, s[22:23]

; __device__ __forceinline__ unsigned xb_ld(unsigned* p)              { return __hip_atomic_load(p, __ATOMIC_RELAXED, __HIP_MEMORY_SCOPE_AGENT); }
; __device__ __forceinline__ unsigned xb_add(unsigned* p, unsigned v) { return __hip_atomic_fetch_add(p, v, __ATOMIC_RELAXED, __HIP_MEMORY_SCOPE_AGENT); }
; #define XB_SPIN(cond, bar) do { unsigned _sp = 0; while (cond) { __builtin_amdgcn_s_sleep(1); \
;     if ((++_sp & 255u) == 0u) { if (xb_ld(&(bar)[XB_TMO])) break; if (_sp > XB_SPIN_CAP) { atomicAdd(&(bar)[XB_TMO], 1u); break; } } } } while (0)
; __device__ __forceinline__ void xcd_barrier(const XcdBarrier& b) {
;     ...
;             else XB_SPIN(xb_ld(&bar[XB_TOPGEN]) == tg, bar);
;             __builtin_amdgcn_fence(__ATOMIC_ACQUIRE, "agent");
;             xb_add(&bar[XB_XGEN(b.x)], 1u);
;             asm volatile("s_waitcnt vmcnt(0)" ::: "memory");
;         } else {
;             XB_SPIN(xb_ld(&bar[XB_XGEN(b.x)]) == gen, bar);
.LBB0_151:
	s_and_b32 s0, s22, 0xff
	s_cmp_lg_u32 s0, 0
	s_mov_b64 s[16:17], -1
	s_nop 0
	s_cbranch_scc0 .LBB0_153
	s_mov_b64 s[18:19], -1
	s_and_saveexec_b64 s[20:21], s[16:17]
	s_cbranch_execz .LBB0_150
	s_branch .LBB0_156

; __device__ __forceinline__ unsigned xb_ld(unsigned* p)              { return __hip_atomic_load(p, __ATOMIC_RELAXED, __HIP_MEMORY_SCOPE_AGENT); }
; __device__ __forceinline__ void xcd_barrier_complete(unsigned* bar, unsigned x, unsigned& nloc, unsigned& nx) {
;     const unsigned G = gridDim.x * gridDim.y * gridDim.z;
;     unsigned sum, cnt, mine, sp = 0u;
;     for (;;) {
;         sum = 0u; cnt = 0u; mine = 0u;
; #pragma unroll
;         for (unsigned j = 0; j < 16; ++j) { const unsigned c = xb_ld(&bar[XB_XCNT(j)]); sum += c; cnt += (c > 0u) ? 1u : 0u; mine = (j == x) ? c : mine; }
;         if (sum == G) break;
;         __builtin_amdgcn_s_sleep(1);
;         if ((++sp & 255u) == 0u) { if (xb_ld(&bar[XB_TMO])) break; if (sp > XB_SPIN_CAP) { atomicAdd(&bar[XB_TMO], 1u); break; } }
;     }
;     nloc = mine > 0u ? mine : 1u; nx = cnt > 0u ? cnt : 1u;
; }
.LBB0_186:
	v_mov_b64_e32 v[2:3], s[6:7]
	s_waitcnt lgkmcnt(0)
	flat_load_dword v0, v[2:3] sc1
	v_mov_b64_e32 v[2:3], s[8:9]
	flat_load_dword v2, v[2:3] sc1
	v_mov_b64_e32 v[4:5], s[10:11]
	flat_load_dword v3, v[4:5] sc1
	v_mov_b64_e32 v[4:5], s[12:13]
	flat_load_dword v4, v[4:5] sc1
	v_readlane_b32 s0, v252, 38
	s_or_b64 s[60:61], s[60:61], exec
	s_or_b64 s[54:55], s[54:55], exec
	s_waitcnt vmcnt(0) lgkmcnt(0)
	v_add_u32_e32 v6, v2, v0
	v_add_u32_e32 v6, v6, v3
	v_add_u32_e32 v8, v6, v4
	v_mov_b64_e32 v[6:7], s[14:15]
	flat_load_dword v5, v[6:7] sc1
	v_mov_b64_e32 v[6:7], s[16:17]
	flat_load_dword v6, v[6:7] sc1
	s_waitcnt vmcnt(0) lgkmcnt(0)
	v_add_u32_e32 v8, v8, v5
	v_add_u32_e32 v10, v8, v6
	v_mov_b64_e32 v[8:9], s[18:19]
	flat_load_dword v7, v[8:9] sc1
	v_mov_b64_e32 v[8:9], s[20:21]
	flat_load_dword v8, v[8:9] sc1
	s_waitcnt vmcnt(0) lgkmcnt(0)
	v_add_u32_e32 v10, v10, v7
	v_add_u32_e32 v12, v10, v8
	v_mov_b64_e32 v[10:11], s[22:23]
	flat_load_dword v9, v[10:11] sc1
	v_mov_b64_e32 v[10:11], s[24:25]
	flat_load_dword v10, v[10:11] sc1
	s_waitcnt vmcnt(0) lgkmcnt(0)
	v_add_u32_e32 v12, v12, v9
	v_add_u32_e32 v14, v12, v10
	v_mov_b64_e32 v[12:13], s[26:27]
	flat_load_dword v11, v[12:13] sc1
	v_mov_b64_e32 v[12:13], s[28:29]
	flat_load_dword v12, v[12:13] sc1
	s_waitcnt vmcnt(0) lgkmcnt(0)
	v_add_u32_e32 v14, v14, v11
	v_add_u32_e32 v16, v14, v12
	v_mov_b64_e32 v[14:15], s[30:31]
	flat_load_dword v13, v[14:15] sc1
	v_mov_b64_e32 v[14:15], s[34:35]
	flat_load_dword v14, v[14:15] sc1
	s_waitcnt vmcnt(0) lgkmcnt(0)
	v_add_u32_e32 v16, v16, v13
	v_add_u32_e32 v18, v16, v14
	v_mov_b64_e32 v[16:17], s[38:39]
	flat_load_dword v15, v[16:17] sc1
	v_mov_b64_e32 v[16:17], s[40:41]
	flat_load_dword v16, v[16:17] sc1
	s_waitcnt vmcnt(0) lgkmcnt(0)
	v_add_u32_e32 v18, v18, v15
	v_add_u32_e32 v17, v18, v16
	v_cmp_ne_u32_e32 vcc, s0, v17
	s_and_saveexec_b64 s[72:73], vcc
	s_cbranch_execz .LBB0_185
	s_and_b32 s0, s85, 0xff
	s_mov_b64 s[76:77], -1
	s_cmp_eq_u32 s0, 0
	s_mov_b64 s[48:49], -1
	s_mov_b64 s[0:1], -1
	s_nop 0
	s_cbranch_scc1 .LBB0_189
	s_and_saveexec_b64 s[44:45], s[48:49]
	s_cbranch_execz .LBB0_184
	s_branch .LBB0_192

; __device__ __forceinline__ unsigned xb_ld(unsigned* p)              { return __hip_atomic_load(p, __ATOMIC_RELAXED, __HIP_MEMORY_SCOPE_AGENT); }
; __device__ __forceinline__ unsigned xb_add(unsigned* p, unsigned v) { return __hip_atomic_fetch_add(p, v, __ATOMIC_RELAXED, __HIP_MEMORY_SCOPE_AGENT); }
; #define XB_SPIN(cond, bar) do { unsigned _sp = 0; while (cond) { __builtin_amdgcn_s_sleep(1); \
;     if ((++_sp & 255u) == 0u) { if (xb_ld(&(bar)[XB_TMO])) break; if (_sp > XB_SPIN_CAP) { atomicAdd(&(bar)[XB_TMO], 1u); break; } } } } while (0)
; __device__ __forceinline__ void xcd_barrier(const XcdBarrier& b) {
;     ...
;             else XB_SPIN(xb_ld(&bar[XB_TOPGEN]) == tg, bar);
;             __builtin_amdgcn_fence(__ATOMIC_ACQUIRE, "agent");
;             xb_add(&bar[XB_XGEN(b.x)], 1u);
;             asm volatile("s_waitcnt vmcnt(0)" ::: "memory");
;         } else {
;             XB_SPIN(xb_ld(&bar[XB_XGEN(b.x)]) == gen, bar);
.LBB0_200:
	s_and_b32 s0, s26, 0xff
	s_mov_b64 s[18:19], -1
	s_cmp_lg_u32 s0, 0
	s_mov_b64 s[0:1], -1
	s_nop 0
	s_cbranch_scc1 .LBB0_204
	v_mov_b64_e32 v[4:5], s[10:11]
	flat_load_dword v0, v[4:5] sc1
	s_mov_b64 s[0:1], 0
	s_mov_b64 s[20:21], -1
	s_waitcnt vmcnt(0) lgkmcnt(0)
	v_cmp_eq_u32_e32 vcc, 0, v0
	s_and_saveexec_b64 s[22:23], vcc
	s_cmp_lt_u32 s26, 0x40001
	s_cselect_b64 s[0:1], -1, 0
	s_xor_b64 s[20:21], exec, -1
	s_and_b64 s[0:1], s[0:1], exec
	s_or_b64 exec, exec, s[22:23]

; __device__ __forceinline__ unsigned xb_ld(unsigned* p)              { return __hip_atomic_load(p, __ATOMIC_RELAXED, __HIP_MEMORY_SCOPE_AGENT); }
; __device__ __forceinline__ unsigned xb_add(unsigned* p, unsigned v) { return __hip_atomic_fetch_add(p, v, __ATOMIC_RELAXED, __HIP_MEMORY_SCOPE_AGENT); }
; #define XB_SPIN(cond, bar) do { unsigned _sp = 0; while (cond) { __builtin_amdgcn_s_sleep(1); \
;     if ((++_sp & 255u) == 0u) { if (xb_ld(&(bar)[XB_TMO])) break; if (_sp > XB_SPIN_CAP) { atomicAdd(&(bar)[XB_TMO], 1u); break; } } } } while (0)
; __device__ __forceinline__ void xcd_barrier(const XcdBarrier& b) {
;     ...
;             else XB_SPIN(xb_ld(&bar[XB_TOPGEN]) == tg, bar);
;             __builtin_amdgcn_fence(__ATOMIC_ACQUIRE, "agent");
;             xb_add(&bar[XB_XGEN(b.x)], 1u);
;             asm volatile("s_waitcnt vmcnt(0)" ::: "memory");
;         } else {
;             XB_SPIN(xb_ld(&bar[XB_XGEN(b.x)]) == gen, bar);
.LBB0_214:
	s_and_b32 s0, s22, 0xff
	s_mov_b64 s[16:17], -1
	s_cmp_lg_u32 s0, 0
	s_mov_b64 s[18:19], -1
	s_nop 0
	s_cbranch_scc0 .LBB0_216
	s_and_saveexec_b64 s[20:21], s[18:19]
	s_cbranch_execz .LBB0_213
	s_branch .LBB0_219

; __device__ __forceinline__ unsigned xb_ld(unsigned* p)              { return __hip_atomic_load(p, __ATOMIC_RELAXED, __HIP_MEMORY_SCOPE_AGENT); }
; __device__ __forceinline__ void xcd_barrier_complete(unsigned* bar, unsigned x, unsigned& nloc, unsigned& nx) {
;     const unsigned G = gridDim.x * gridDim.y * gridDim.z;
;     unsigned sum, cnt, mine, sp = 0u;
;     for (;;) {
;         sum = 0u; cnt = 0u; mine = 0u;
; #pragma unroll
;         for (unsigned j = 0; j < 16; ++j) { const unsigned c = xb_ld(&bar[XB_XCNT(j)]); sum += c; cnt += (c > 0u) ? 1u : 0u; mine = (j == x) ? c : mine; }
;         if (sum == G) break;
;         __builtin_amdgcn_s_sleep(1);
;         if ((++sp & 255u) == 0u) { if (xb_ld(&bar[XB_TMO])) break; if (sp > XB_SPIN_CAP) { atomicAdd(&bar[XB_TMO], 1u); break; } }
;     }
;     nloc = mine > 0u ? mine : 1u; nx = cnt > 0u ? cnt : 1u;
; }
.LBB0_348:
	v_mov_b64_e32 v[2:3], s[8:9]
	s_waitcnt lgkmcnt(0)
	flat_load_dword v0, v[2:3] sc1
	v_mov_b64_e32 v[2:3], s[10:11]
	flat_load_dword v2, v[2:3] sc1
	v_mov_b64_e32 v[4:5], s[12:13]
	flat_load_dword v3, v[4:5] sc1
	v_mov_b64_e32 v[4:5], s[14:15]
	flat_load_dword v4, v[4:5] sc1
	v_readlane_b32 s0, v252, 38
	s_or_b64 s[76:77], s[76:77], exec
	s_or_b64 s[72:73], s[72:73], exec
	s_waitcnt vmcnt(0) lgkmcnt(0)
	v_add_u32_e32 v6, v2, v0
	v_add_u32_e32 v6, v6, v3
	v_add_u32_e32 v8, v6, v4
	v_mov_b64_e32 v[6:7], s[16:17]
	flat_load_dword v5, v[6:7] sc1
	v_mov_b64_e32 v[6:7], s[18:19]
	flat_load_dword v6, v[6:7] sc1
	s_waitcnt vmcnt(0) lgkmcnt(0)
	v_add_u32_e32 v8, v8, v5
	v_add_u32_e32 v10, v8, v6
	v_mov_b64_e32 v[8:9], s[20:21]
	flat_load_dword v7, v[8:9] sc1
	v_mov_b64_e32 v[8:9], s[22:23]
	flat_load_dword v8, v[8:9] sc1
	s_waitcnt vmcnt(0) lgkmcnt(0)
	v_add_u32_e32 v10, v10, v7
	v_add_u32_e32 v12, v10, v8
	v_mov_b64_e32 v[10:11], s[24:25]
	flat_load_dword v9, v[10:11] sc1
	v_mov_b64_e32 v[10:11], s[26:27]
	flat_load_dword v10, v[10:11] sc1
	s_waitcnt vmcnt(0) lgkmcnt(0)
	v_add_u32_e32 v12, v12, v9
	v_add_u32_e32 v14, v12, v10
	v_mov_b64_e32 v[12:13], s[28:29]
	flat_load_dword v11, v[12:13] sc1
	v_mov_b64_e32 v[12:13], s[30:31]
	flat_load_dword v12, v[12:13] sc1
	s_waitcnt vmcnt(0) lgkmcnt(0)
	v_add_u32_e32 v14, v14, v11
	v_add_u32_e32 v16, v14, v12
	v_mov_b64_e32 v[14:15], s[34:35]
	flat_load_dword v13, v[14:15] sc1
	v_mov_b64_e32 v[14:15], s[36:37]
	flat_load_dword v14, v[14:15] sc1
	s_waitcnt vmcnt(0) lgkmcnt(0)
	v_add_u32_e32 v16, v16, v13
	v_add_u32_e32 v18, v16, v14
	v_mov_b64_e32 v[16:17], s[40:41]
	flat_load_dword v15, v[16:17] sc1
	v_mov_b64_e32 v[16:17], s[42:43]
	flat_load_dword v16, v[16:17] sc1
	s_waitcnt vmcnt(0) lgkmcnt(0)
	v_add_u32_e32 v18, v18, v15
	v_add_u32_e32 v17, v18, v16
	v_cmp_ne_u32_e32 vcc, s0, v17
	s_and_saveexec_b64 s[4:5], vcc
	s_cbranch_execz .LBB0_347
	s_and_b32 s0, s55, 0xff
	s_mov_b64 s[90:91], -1
	s_cmp_eq_u32 s0, 0
	s_mov_b64 s[48:49], -1
	s_mov_b64 s[0:1], -1
	s_nop 0
	s_cbranch_scc1 .LBB0_351
	s_and_saveexec_b64 s[44:45], s[48:49]
	s_cbranch_execz .LBB0_346
	s_branch .LBB0_354

; __device__ __forceinline__ unsigned xb_ld(unsigned* p)              { return __hip_atomic_load(p, __ATOMIC_RELAXED, __HIP_MEMORY_SCOPE_AGENT); }
; __device__ __forceinline__ void xcd_barrier_complete(unsigned* bar, unsigned x, unsigned& nloc, unsigned& nx) {
;     const unsigned G = gridDim.x * gridDim.y * gridDim.z;
;     unsigned sum, cnt, mine, sp = 0u;
;     for (;;) {
;         sum = 0u; cnt = 0u; mine = 0u;
; #pragma unroll
;         for (unsigned j = 0; j < 16; ++j) { const unsigned c = xb_ld(&bar[XB_XCNT(j)]); sum += c; cnt += (c > 0u) ? 1u : 0u; mine = (j == x) ? c : mine; }
;         if (sum == G) break;
;         __builtin_amdgcn_s_sleep(1);
;         if ((++sp & 255u) == 0u) { if (xb_ld(&bar[XB_TMO])) break; if (sp > XB_SPIN_CAP) { atomicAdd(&bar[XB_TMO], 1u); break; } }
;     }
;     nloc = mine > 0u ? mine : 1u; nx = cnt > 0u ? cnt : 1u;
; }
.LBB0_435:
	v_mov_b64_e32 v[2:3], s[8:9]
	s_waitcnt lgkmcnt(0)
	flat_load_dword v0, v[2:3] sc1
	v_mov_b64_e32 v[2:3], s[10:11]
	flat_load_dword v2, v[2:3] sc1
	v_mov_b64_e32 v[4:5], s[12:13]
	flat_load_dword v3, v[4:5] sc1
	v_mov_b64_e32 v[4:5], s[14:15]
	flat_load_dword v4, v[4:5] sc1
	v_readlane_b32 s0, v252, 38
	s_or_b64 s[90:91], s[90:91], exec
	s_or_b64 s[76:77], s[76:77], exec
	s_waitcnt vmcnt(0) lgkmcnt(0)
	v_add_u32_e32 v6, v2, v0
	v_add_u32_e32 v6, v6, v3
	v_add_u32_e32 v8, v6, v4
	v_mov_b64_e32 v[6:7], s[16:17]
	flat_load_dword v5, v[6:7] sc1
	v_mov_b64_e32 v[6:7], s[18:19]
	flat_load_dword v6, v[6:7] sc1
	s_waitcnt vmcnt(0) lgkmcnt(0)
	v_add_u32_e32 v8, v8, v5
	v_add_u32_e32 v10, v8, v6
	v_mov_b64_e32 v[8:9], s[20:21]
	flat_load_dword v7, v[8:9] sc1
	v_mov_b64_e32 v[8:9], s[22:23]
	flat_load_dword v8, v[8:9] sc1
	s_waitcnt vmcnt(0) lgkmcnt(0)
	v_add_u32_e32 v10, v10, v7
	v_add_u32_e32 v12, v10, v8
	v_mov_b64_e32 v[10:11], s[24:25]
	flat_load_dword v9, v[10:11] sc1
	v_mov_b64_e32 v[10:11], s[26:27]
	flat_load_dword v10, v[10:11] sc1
	s_waitcnt vmcnt(0) lgkmcnt(0)
	v_add_u32_e32 v12, v12, v9
	v_add_u32_e32 v14, v12, v10
	v_mov_b64_e32 v[12:13], s[28:29]
	flat_load_dword v11, v[12:13] sc1
	v_mov_b64_e32 v[12:13], s[30:31]
	flat_load_dword v12, v[12:13] sc1
	s_waitcnt vmcnt(0) lgkmcnt(0)
	v_add_u32_e32 v14, v14, v11
	v_add_u32_e32 v16, v14, v12
	v_mov_b64_e32 v[14:15], s[34:35]
	flat_load_dword v13, v[14:15] sc1
	v_mov_b64_e32 v[14:15], s[36:37]
	flat_load_dword v14, v[14:15] sc1
	s_waitcnt vmcnt(0) lgkmcnt(0)
	v_add_u32_e32 v16, v16, v13
	v_add_u32_e32 v18, v16, v14
	v_mov_b64_e32 v[16:17], s[42:43]
	flat_load_dword v15, v[16:17] sc1
	v_mov_b64_e32 v[16:17], s[52:53]
	flat_load_dword v16, v[16:17] sc1
	s_waitcnt vmcnt(0) lgkmcnt(0)
	v_add_u32_e32 v18, v18, v15
	v_add_u32_e32 v17, v18, v16
	v_cmp_ne_u32_e32 vcc, s0, v17
	s_and_saveexec_b64 s[4:5], vcc
	s_cbranch_execz .LBB0_434
	s_and_b32 s0, s84, 0xff
	s_mov_b64 s[94:95], -1
	s_cmp_eq_u32 s0, 0
	s_mov_b64 s[48:49], -1
	s_mov_b64 s[0:1], -1
	s_nop 0
	s_cbranch_scc1 .LBB0_438
	s_and_saveexec_b64 s[44:45], s[48:49]
	s_cbranch_execz .LBB0_433
	s_branch .LBB0_441

; __device__ __forceinline__ unsigned xb_ld(unsigned* p)              { return __hip_atomic_load(p, __ATOMIC_RELAXED, __HIP_MEMORY_SCOPE_AGENT); }
; __device__ __forceinline__ void xcd_barrier_complete(unsigned* bar, unsigned x, unsigned& nloc, unsigned& nx) {
;     const unsigned G = gridDim.x * gridDim.y * gridDim.z;
;     unsigned sum, cnt, mine, sp = 0u;
;     for (;;) {
;         sum = 0u; cnt = 0u; mine = 0u;
; #pragma unroll
;         for (unsigned j = 0; j < 16; ++j) { const unsigned c = xb_ld(&bar[XB_XCNT(j)]); sum += c; cnt += (c > 0u) ? 1u : 0u; mine = (j == x) ? c : mine; }
;         if (sum == G) break;
;         __builtin_amdgcn_s_sleep(1);
;         if ((++sp & 255u) == 0u) { if (xb_ld(&bar[XB_TMO])) break; if (sp > XB_SPIN_CAP) { atomicAdd(&bar[XB_TMO], 1u); break; } }
;     }
;     nloc = mine > 0u ? mine : 1u; nx = cnt > 0u ? cnt : 1u;
; }
.LBB0_626:
	v_mov_b64_e32 v[2:3], s[8:9]
	s_waitcnt lgkmcnt(0)
	flat_load_dword v0, v[2:3] sc1
	v_mov_b64_e32 v[2:3], s[10:11]
	flat_load_dword v2, v[2:3] sc1
	v_mov_b64_e32 v[4:5], s[12:13]
	flat_load_dword v3, v[4:5] sc1
	v_mov_b64_e32 v[4:5], s[14:15]
	flat_load_dword v4, v[4:5] sc1
	v_readlane_b32 s0, v252, 38
	s_or_b64 s[96:97], s[96:97], exec
	s_or_b64 s[94:95], s[94:95], exec
	s_waitcnt vmcnt(0) lgkmcnt(0)
	v_add_u32_e32 v6, v2, v0
	v_add_u32_e32 v6, v6, v3
	v_add_u32_e32 v8, v6, v4
	v_mov_b64_e32 v[6:7], s[16:17]
	flat_load_dword v5, v[6:7] sc1
	v_mov_b64_e32 v[6:7], s[18:19]
	flat_load_dword v6, v[6:7] sc1
	s_waitcnt vmcnt(0) lgkmcnt(0)
	v_add_u32_e32 v8, v8, v5
	v_add_u32_e32 v10, v8, v6
	v_mov_b64_e32 v[8:9], s[20:21]
	flat_load_dword v7, v[8:9] sc1
	v_mov_b64_e32 v[8:9], s[22:23]
	flat_load_dword v8, v[8:9] sc1
	s_waitcnt vmcnt(0) lgkmcnt(0)
	v_add_u32_e32 v10, v10, v7
	v_add_u32_e32 v12, v10, v8
	v_mov_b64_e32 v[10:11], s[24:25]
	flat_load_dword v9, v[10:11] sc1
	v_mov_b64_e32 v[10:11], s[26:27]
	flat_load_dword v10, v[10:11] sc1
	s_waitcnt vmcnt(0) lgkmcnt(0)
	v_add_u32_e32 v12, v12, v9
	v_add_u32_e32 v14, v12, v10
	v_mov_b64_e32 v[12:13], s[28:29]
	flat_load_dword v11, v[12:13] sc1
	v_mov_b64_e32 v[12:13], s[30:31]
	flat_load_dword v12, v[12:13] sc1
	s_waitcnt vmcnt(0) lgkmcnt(0)
	v_add_u32_e32 v14, v14, v11
	v_add_u32_e32 v16, v14, v12
	v_mov_b64_e32 v[14:15], s[34:35]
	flat_load_dword v13, v[14:15] sc1
	v_mov_b64_e32 v[14:15], s[36:37]
	flat_load_dword v14, v[14:15] sc1
	s_waitcnt vmcnt(0) lgkmcnt(0)
	v_add_u32_e32 v16, v16, v13
	v_add_u32_e32 v18, v16, v14
	v_mov_b64_e32 v[16:17], s[60:61]
	flat_load_dword v15, v[16:17] sc1
	v_mov_b64_e32 v[16:17], s[72:73]
	flat_load_dword v16, v[16:17] sc1
	s_waitcnt vmcnt(0) lgkmcnt(0)
	v_add_u32_e32 v18, v18, v15
	v_add_u32_e32 v17, v18, v16
	v_cmp_ne_u32_e32 vcc, s0, v17
	s_and_saveexec_b64 s[4:5], vcc
	s_cbranch_execz .LBB0_625
	s_and_b32 s44, s55, 0xff
	s_mov_b64 s[0:1], -1
	s_cmp_eq_u32 s44, 0
	s_mov_b64 s[44:45], -1
	s_mov_b64 s[48:49], -1
	s_nop 0
	s_cbranch_scc1 .LBB0_629
	s_and_saveexec_b64 s[84:85], s[44:45]
	s_cbranch_execz .LBB0_624
	s_branch .LBB0_632

; __device__ __forceinline__ unsigned xb_ld(unsigned* p)              { return __hip_atomic_load(p, __ATOMIC_RELAXED, __HIP_MEMORY_SCOPE_AGENT); }
; __device__ __forceinline__ unsigned xb_add(unsigned* p, unsigned v) { return __hip_atomic_fetch_add(p, v, __ATOMIC_RELAXED, __HIP_MEMORY_SCOPE_AGENT); }
; #define XB_SPIN(cond, bar) do { unsigned _sp = 0; while (cond) { __builtin_amdgcn_s_sleep(1); \
;     if ((++_sp & 255u) == 0u) { if (xb_ld(&(bar)[XB_TMO])) break; if (_sp > XB_SPIN_CAP) { atomicAdd(&(bar)[XB_TMO], 1u); break; } } } } while (0)
; __device__ __forceinline__ void xcd_barrier(const XcdBarrier& b) {
;     ...
;             else XB_SPIN(xb_ld(&bar[XB_TOPGEN]) == tg, bar);
;             __builtin_amdgcn_fence(__ATOMIC_ACQUIRE, "agent");
;             xb_add(&bar[XB_XGEN(b.x)], 1u);
;             asm volatile("s_waitcnt vmcnt(0)" ::: "memory");
;         } else {
;             XB_SPIN(xb_ld(&bar[XB_XGEN(b.x)]) == gen, bar);
.LBB0_654:
	s_and_b32 s16, s22, 0xff
	s_mov_b64 s[0:1], -1
	s_cmp_lg_u32 s16, 0
	s_mov_b64 s[18:19], -1
	s_nop 0
	s_cbranch_scc0 .LBB0_656
	s_and_saveexec_b64 s[20:21], s[18:19]
	s_cbranch_execz .LBB0_653
	s_branch .LBB0_659

; __device__ __forceinline__ unsigned xb_ld(unsigned* p)              { return __hip_atomic_load(p, __ATOMIC_RELAXED, __HIP_MEMORY_SCOPE_AGENT); }
; __device__ __forceinline__ void xcd_barrier_complete(unsigned* bar, unsigned x, unsigned& nloc, unsigned& nx) {
;     const unsigned G = gridDim.x * gridDim.y * gridDim.z;
;     unsigned sum, cnt, mine, sp = 0u;
;     for (;;) {
;         sum = 0u; cnt = 0u; mine = 0u;
; #pragma unroll
;         for (unsigned j = 0; j < 16; ++j) { const unsigned c = xb_ld(&bar[XB_XCNT(j)]); sum += c; cnt += (c > 0u) ? 1u : 0u; mine = (j == x) ? c : mine; }
;         if (sum == G) break;
;         __builtin_amdgcn_s_sleep(1);
;         if ((++sp & 255u) == 0u) { if (xb_ld(&bar[XB_TMO])) break; if (sp > XB_SPIN_CAP) { atomicAdd(&bar[XB_TMO], 1u); break; } }
;     }
;     nloc = mine > 0u ? mine : 1u; nx = cnt > 0u ? cnt : 1u;
; }
.LBB0_888:
	v_mov_b64_e32 v[2:3], s[8:9]
	s_waitcnt lgkmcnt(0)
	flat_load_dword v0, v[2:3] sc1
	v_mov_b64_e32 v[2:3], s[10:11]
	flat_load_dword v2, v[2:3] sc1
	v_mov_b64_e32 v[4:5], s[12:13]
	flat_load_dword v3, v[4:5] sc1
	v_mov_b64_e32 v[4:5], s[14:15]
	flat_load_dword v4, v[4:5] sc1
	v_readlane_b32 s0, v252, 38
	s_or_b64 s[90:91], s[90:91], exec
	s_or_b64 s[76:77], s[76:77], exec
	s_waitcnt vmcnt(0) lgkmcnt(0)
	v_add_u32_e32 v6, v2, v0
	v_add_u32_e32 v6, v6, v3
	v_add_u32_e32 v8, v6, v4
	v_mov_b64_e32 v[6:7], s[16:17]
	flat_load_dword v5, v[6:7] sc1
	v_mov_b64_e32 v[6:7], s[18:19]
	flat_load_dword v6, v[6:7] sc1
	s_waitcnt vmcnt(0) lgkmcnt(0)
	v_add_u32_e32 v8, v8, v5
	v_add_u32_e32 v10, v8, v6
	v_mov_b64_e32 v[8:9], s[20:21]
	flat_load_dword v7, v[8:9] sc1
	v_mov_b64_e32 v[8:9], s[22:23]
	flat_load_dword v8, v[8:9] sc1
	s_waitcnt vmcnt(0) lgkmcnt(0)
	v_add_u32_e32 v10, v10, v7
	v_add_u32_e32 v12, v10, v8
	v_mov_b64_e32 v[10:11], s[24:25]
	flat_load_dword v9, v[10:11] sc1
	v_mov_b64_e32 v[10:11], s[26:27]
	flat_load_dword v10, v[10:11] sc1
	s_waitcnt vmcnt(0) lgkmcnt(0)
	v_add_u32_e32 v12, v12, v9
	v_add_u32_e32 v14, v12, v10
	v_mov_b64_e32 v[12:13], s[28:29]
	flat_load_dword v11, v[12:13] sc1
	v_mov_b64_e32 v[12:13], s[30:31]
	flat_load_dword v12, v[12:13] sc1
	s_waitcnt vmcnt(0) lgkmcnt(0)
	v_add_u32_e32 v14, v14, v11
	v_add_u32_e32 v16, v14, v12
	v_mov_b64_e32 v[14:15], s[34:35]
	flat_load_dword v13, v[14:15] sc1
	v_mov_b64_e32 v[14:15], s[36:37]
	flat_load_dword v14, v[14:15] sc1
	s_waitcnt vmcnt(0) lgkmcnt(0)
	v_add_u32_e32 v16, v16, v13
	v_add_u32_e32 v18, v16, v14
	v_mov_b64_e32 v[16:17], s[42:43]
	flat_load_dword v15, v[16:17] sc1
	v_mov_b64_e32 v[16:17], s[52:53]
	flat_load_dword v16, v[16:17] sc1
	s_waitcnt vmcnt(0) lgkmcnt(0)
	v_add_u32_e32 v18, v18, v15
	v_add_u32_e32 v17, v18, v16
	v_cmp_ne_u32_e32 vcc, s0, v17
	s_and_saveexec_b64 s[4:5], vcc
	s_cbranch_execz .LBB0_887
	s_and_b32 s44, s62, 0xff
	s_mov_b64 s[0:1], -1
	s_cmp_eq_u32 s44, 0
	s_mov_b64 s[44:45], -1
	s_mov_b64 s[48:49], -1
	s_nop 0
	s_cbranch_scc1 .LBB0_891
	s_and_saveexec_b64 s[84:85], s[44:45]
	s_cbranch_execz .LBB0_886
	s_branch .LBB0_894

; __device__ __forceinline__ unsigned xb_ld(unsigned* p)              { return __hip_atomic_load(p, __ATOMIC_RELAXED, __HIP_MEMORY_SCOPE_AGENT); }
; __device__ __forceinline__ void xcd_barrier_complete(unsigned* bar, unsigned x, unsigned& nloc, unsigned& nx) {
;     const unsigned G = gridDim.x * gridDim.y * gridDim.z;
;     unsigned sum, cnt, mine, sp = 0u;
;     for (;;) {
;         sum = 0u; cnt = 0u; mine = 0u;
; #pragma unroll
;         for (unsigned j = 0; j < 16; ++j) { const unsigned c = xb_ld(&bar[XB_XCNT(j)]); sum += c; cnt += (c > 0u) ? 1u : 0u; mine = (j == x) ? c : mine; }
;         if (sum == G) break;
;         __builtin_amdgcn_s_sleep(1);
;         if ((++sp & 255u) == 0u) { if (xb_ld(&bar[XB_TMO])) break; if (sp > XB_SPIN_CAP) { atomicAdd(&bar[XB_TMO], 1u); break; } }
;     }
;     nloc = mine > 0u ? mine : 1u; nx = cnt > 0u ? cnt : 1u;
; }
.LBB0_983:
	v_mov_b64_e32 v[2:3], s[8:9]
	s_waitcnt lgkmcnt(0)
	flat_load_dword v0, v[2:3] sc1
	v_mov_b64_e32 v[2:3], s[10:11]
	flat_load_dword v2, v[2:3] sc1
	v_mov_b64_e32 v[4:5], s[12:13]
	flat_load_dword v3, v[4:5] sc1
	v_mov_b64_e32 v[4:5], s[14:15]
	flat_load_dword v4, v[4:5] sc1
	v_readlane_b32 s0, v252, 38
	s_or_b64 s[76:77], s[76:77], exec
	s_or_b64 s[72:73], s[72:73], exec
	s_waitcnt vmcnt(0) lgkmcnt(0)
	v_add_u32_e32 v6, v2, v0
	v_add_u32_e32 v6, v6, v3
	v_add_u32_e32 v8, v6, v4
	v_mov_b64_e32 v[6:7], s[16:17]
	flat_load_dword v5, v[6:7] sc1
	v_mov_b64_e32 v[6:7], s[18:19]
	flat_load_dword v6, v[6:7] sc1
	s_waitcnt vmcnt(0) lgkmcnt(0)
	v_add_u32_e32 v8, v8, v5
	v_add_u32_e32 v10, v8, v6
	v_mov_b64_e32 v[8:9], s[20:21]
	flat_load_dword v7, v[8:9] sc1
	v_mov_b64_e32 v[8:9], s[22:23]
	flat_load_dword v8, v[8:9] sc1
	s_waitcnt vmcnt(0) lgkmcnt(0)
	v_add_u32_e32 v10, v10, v7
	v_add_u32_e32 v12, v10, v8
	v_mov_b64_e32 v[10:11], s[24:25]
	flat_load_dword v9, v[10:11] sc1
	v_mov_b64_e32 v[10:11], s[26:27]
	flat_load_dword v10, v[10:11] sc1
	s_waitcnt vmcnt(0) lgkmcnt(0)
	v_add_u32_e32 v12, v12, v9
	v_add_u32_e32 v14, v12, v10
	v_mov_b64_e32 v[12:13], s[28:29]
	flat_load_dword v11, v[12:13] sc1
	v_mov_b64_e32 v[12:13], s[30:31]
	flat_load_dword v12, v[12:13] sc1
	s_waitcnt vmcnt(0) lgkmcnt(0)
	v_add_u32_e32 v14, v14, v11
	v_add_u32_e32 v16, v14, v12
	v_mov_b64_e32 v[14:15], s[34:35]
	flat_load_dword v13, v[14:15] sc1
	v_mov_b64_e32 v[14:15], s[36:37]
	flat_load_dword v14, v[14:15] sc1
	s_waitcnt vmcnt(0) lgkmcnt(0)
	v_add_u32_e32 v16, v16, v13
	v_add_u32_e32 v18, v16, v14
	v_mov_b64_e32 v[16:17], s[42:43]
	flat_load_dword v15, v[16:17] sc1
	v_mov_b64_e32 v[16:17], s[52:53]
	flat_load_dword v16, v[16:17] sc1
	s_waitcnt vmcnt(0) lgkmcnt(0)
	v_add_u32_e32 v18, v18, v15
	v_add_u32_e32 v17, v18, v16
	v_cmp_ne_u32_e32 vcc, s0, v17
	s_and_saveexec_b64 s[4:5], vcc
	s_cbranch_execz .LBB0_982
	s_and_b32 s44, s95, 0xff
	s_mov_b64 s[0:1], -1
	s_cmp_eq_u32 s44, 0
	s_mov_b64 s[44:45], -1
	s_mov_b64 s[48:49], -1
	s_nop 0
	s_cbranch_scc1 .LBB0_986
	s_and_saveexec_b64 s[78:79], s[44:45]
	s_cbranch_execz .LBB0_981
	s_branch .LBB0_989

; __device__ __forceinline__ unsigned xb_ld(unsigned* p)              { return __hip_atomic_load(p, __ATOMIC_RELAXED, __HIP_MEMORY_SCOPE_AGENT); }
; __device__ __forceinline__ void xcd_barrier_complete(unsigned* bar, unsigned x, unsigned& nloc, unsigned& nx) {
;     const unsigned G = gridDim.x * gridDim.y * gridDim.z;
;     unsigned sum, cnt, mine, sp = 0u;
;     for (;;) {
;         sum = 0u; cnt = 0u; mine = 0u;
; #pragma unroll
;         for (unsigned j = 0; j < 16; ++j) { const unsigned c = xb_ld(&bar[XB_XCNT(j)]); sum += c; cnt += (c > 0u) ? 1u : 0u; mine = (j == x) ? c : mine; }
;         if (sum == G) break;
;         __builtin_amdgcn_s_sleep(1);
;         if ((++sp & 255u) == 0u) { if (xb_ld(&bar[XB_TMO])) break; if (sp > XB_SPIN_CAP) { atomicAdd(&bar[XB_TMO], 1u); break; } }
;     }
;     nloc = mine > 0u ? mine : 1u; nx = cnt > 0u ? cnt : 1u;
; }
.LBB0_1044:
	v_mov_b64_e32 v[2:3], s[8:9]
	s_waitcnt lgkmcnt(0)
	flat_load_dword v0, v[2:3] sc1
	v_mov_b64_e32 v[2:3], s[10:11]
	flat_load_dword v2, v[2:3] sc1
	v_mov_b64_e32 v[4:5], s[12:13]
	flat_load_dword v3, v[4:5] sc1
	v_mov_b64_e32 v[4:5], s[14:15]
	flat_load_dword v4, v[4:5] sc1
	v_readlane_b32 s0, v252, 38
	s_or_b64 s[76:77], s[76:77], exec
	s_or_b64 s[72:73], s[72:73], exec
	s_waitcnt vmcnt(0) lgkmcnt(0)
	v_add_u32_e32 v6, v2, v0
	v_add_u32_e32 v6, v6, v3
	v_add_u32_e32 v8, v6, v4
	v_mov_b64_e32 v[6:7], s[16:17]
	flat_load_dword v5, v[6:7] sc1
	v_mov_b64_e32 v[6:7], s[18:19]
	flat_load_dword v6, v[6:7] sc1
	s_waitcnt vmcnt(0) lgkmcnt(0)
	v_add_u32_e32 v8, v8, v5
	v_add_u32_e32 v10, v8, v6
	v_mov_b64_e32 v[8:9], s[20:21]
	flat_load_dword v7, v[8:9] sc1
	v_mov_b64_e32 v[8:9], s[22:23]
	flat_load_dword v8, v[8:9] sc1
	s_waitcnt vmcnt(0) lgkmcnt(0)
	v_add_u32_e32 v10, v10, v7
	v_add_u32_e32 v12, v10, v8
	v_mov_b64_e32 v[10:11], s[24:25]
	flat_load_dword v9, v[10:11] sc1
	v_mov_b64_e32 v[10:11], s[26:27]
	flat_load_dword v10, v[10:11] sc1
	s_waitcnt vmcnt(0) lgkmcnt(0)
	v_add_u32_e32 v12, v12, v9
	v_add_u32_e32 v14, v12, v10
	v_mov_b64_e32 v[12:13], s[28:29]
	flat_load_dword v11, v[12:13] sc1
	v_mov_b64_e32 v[12:13], s[30:31]
	flat_load_dword v12, v[12:13] sc1
	s_waitcnt vmcnt(0) lgkmcnt(0)
	v_add_u32_e32 v14, v14, v11
	v_add_u32_e32 v16, v14, v12
	v_mov_b64_e32 v[14:15], s[34:35]
	flat_load_dword v13, v[14:15] sc1
	v_mov_b64_e32 v[14:15], s[36:37]
	flat_load_dword v14, v[14:15] sc1
	s_waitcnt vmcnt(0) lgkmcnt(0)
	v_add_u32_e32 v16, v16, v13
	v_add_u32_e32 v18, v16, v14
	v_mov_b64_e32 v[16:17], s[42:43]
	flat_load_dword v15, v[16:17] sc1
	v_mov_b64_e32 v[16:17], s[52:53]
	flat_load_dword v16, v[16:17] sc1
	s_waitcnt vmcnt(0) lgkmcnt(0)
	v_add_u32_e32 v18, v18, v15
	v_add_u32_e32 v17, v18, v16
	v_cmp_ne_u32_e32 vcc, s0, v17
	s_and_saveexec_b64 s[4:5], vcc
	s_cbranch_execz .LBB0_1043
	s_and_b32 s44, s94, 0xff
	s_mov_b64 s[0:1], -1
	s_cmp_eq_u32 s44, 0
	s_mov_b64 s[44:45], -1
	s_mov_b64 s[48:49], -1
	s_nop 0
	s_cbranch_scc1 .LBB0_1047
	s_and_saveexec_b64 s[78:79], s[44:45]
	s_cbranch_execz .LBB0_1042
	s_branch .LBB0_1050

; __device__ __forceinline__ unsigned xb_ld(unsigned* p)              { return __hip_atomic_load(p, __ATOMIC_RELAXED, __HIP_MEMORY_SCOPE_AGENT); }
; __device__ __forceinline__ void xcd_barrier_complete(unsigned* bar, unsigned x, unsigned& nloc, unsigned& nx) {
;     const unsigned G = gridDim.x * gridDim.y * gridDim.z;
;     unsigned sum, cnt, mine, sp = 0u;
;     for (;;) {
;         sum = 0u; cnt = 0u; mine = 0u;
; #pragma unroll
;         for (unsigned j = 0; j < 16; ++j) { const unsigned c = xb_ld(&bar[XB_XCNT(j)]); sum += c; cnt += (c > 0u) ? 1u : 0u; mine = (j == x) ? c : mine; }
;         if (sum == G) break;
;         __builtin_amdgcn_s_sleep(1);
;         if ((++sp & 255u) == 0u) { if (xb_ld(&bar[XB_TMO])) break; if (sp > XB_SPIN_CAP) { atomicAdd(&bar[XB_TMO], 1u); break; } }
;     }
;     nloc = mine > 0u ? mine : 1u; nx = cnt > 0u ? cnt : 1u;
; }
.LBB0_1131:
	v_mov_b64_e32 v[2:3], s[6:7]
	s_waitcnt lgkmcnt(0)
	flat_load_dword v0, v[2:3] sc1
	v_mov_b64_e32 v[2:3], s[8:9]
	flat_load_dword v2, v[2:3] sc1
	v_mov_b64_e32 v[4:5], s[10:11]
	flat_load_dword v3, v[4:5] sc1
	v_mov_b64_e32 v[4:5], s[12:13]
	flat_load_dword v4, v[4:5] sc1
	v_readlane_b32 s0, v252, 38
	s_or_b64 s[60:61], s[60:61], exec
	s_or_b64 s[54:55], s[54:55], exec
	s_waitcnt vmcnt(0) lgkmcnt(0)
	v_add_u32_e32 v6, v2, v0
	v_add_u32_e32 v6, v6, v3
	v_add_u32_e32 v8, v6, v4
	v_mov_b64_e32 v[6:7], s[14:15]
	flat_load_dword v5, v[6:7] sc1
	v_mov_b64_e32 v[6:7], s[16:17]
	flat_load_dword v6, v[6:7] sc1
	s_waitcnt vmcnt(0) lgkmcnt(0)
	v_add_u32_e32 v8, v8, v5
	v_add_u32_e32 v10, v8, v6
	v_mov_b64_e32 v[8:9], s[18:19]
	flat_load_dword v7, v[8:9] sc1
	v_mov_b64_e32 v[8:9], s[20:21]
	flat_load_dword v8, v[8:9] sc1
	s_waitcnt vmcnt(0) lgkmcnt(0)
	v_add_u32_e32 v10, v10, v7
	v_add_u32_e32 v12, v10, v8
	v_mov_b64_e32 v[10:11], s[22:23]
	flat_load_dword v9, v[10:11] sc1
	v_mov_b64_e32 v[10:11], s[24:25]
	flat_load_dword v10, v[10:11] sc1
	s_waitcnt vmcnt(0) lgkmcnt(0)
	v_add_u32_e32 v12, v12, v9
	v_add_u32_e32 v14, v12, v10
	v_mov_b64_e32 v[12:13], s[26:27]
	flat_load_dword v11, v[12:13] sc1
	v_mov_b64_e32 v[12:13], s[28:29]
	flat_load_dword v12, v[12:13] sc1
	s_waitcnt vmcnt(0) lgkmcnt(0)
	v_add_u32_e32 v14, v14, v11
	v_add_u32_e32 v16, v14, v12
	v_mov_b64_e32 v[14:15], s[30:31]
	flat_load_dword v13, v[14:15] sc1
	v_mov_b64_e32 v[14:15], s[34:35]
	flat_load_dword v14, v[14:15] sc1
	s_waitcnt vmcnt(0) lgkmcnt(0)
	v_add_u32_e32 v16, v16, v13
	v_add_u32_e32 v18, v16, v14
	v_mov_b64_e32 v[16:17], s[38:39]
	flat_load_dword v15, v[16:17] sc1
	v_mov_b64_e32 v[16:17], s[40:41]
	flat_load_dword v16, v[16:17] sc1
	s_waitcnt vmcnt(0) lgkmcnt(0)
	v_add_u32_e32 v18, v18, v15
	v_add_u32_e32 v17, v18, v16
	v_cmp_ne_u32_e32 vcc, s0, v17
	s_and_saveexec_b64 s[72:73], vcc
	s_cbranch_execz .LBB0_1130
	s_and_b32 s44, s78, 0xff
	s_mov_b64 s[0:1], -1
	s_cmp_eq_u32 s44, 0
	s_mov_b64 s[44:45], -1
	s_mov_b64 s[48:49], -1
	s_nop 0
	s_cbranch_scc1 .LBB0_1134
	s_and_saveexec_b64 s[76:77], s[44:45]
	s_cbranch_execz .LBB0_1129
	s_branch .LBB0_1137

.LBB0_1181:
	s_nop 0
	global_load_dword v3, v1, s[6:7] offset:32 sc1
	s_waitcnt vmcnt(0)
	v_and_b32_e32 v3, 0xffff0000, v3
	v_cmp_ne_u32_e32 vcc, v3, v2
	s_or_b64 s[0:1], vcc, s[0:1]
	s_andn2_b64 exec, exec, s[0:1]
	s_cbranch_execnz .LBB0_1181
